# phase-8 gate/up GEMM: same ssq prefetch (first half at K-loop start, second half at epilogue start)
# baseline (speedup 1.0000x reference)
.LBB0_1356:
	s_ashr_i32 s15, s14, 31
	s_lshl_b64 s[16:17], s[14:15], 19
	s_add_u32 s16, s60, s16
	s_addc_u32 s17, s61, s17
	s_and_b64 s[18:19], s[0:1], exec
	s_cselect_b32 s15, s17, s25
	s_cselect_b32 s72, s16, s24
	s_ashr_i32 s13, s12, 31
	s_lshl_b64 s[18:19], s[12:13], 19
	s_add_u32 s18, s44, s18
	s_addc_u32 s19, s45, s19
	s_and_b64 s[28:29], s[0:1], exec
	s_cselect_b32 s13, s19, s27
	s_cselect_b32 s73, s18, s26
	s_add_u32 s24, s24, 0x40080
	s_addc_u32 s25, s25, 0
	s_add_u32 s74, s26, 0x100
	v_mov_b32_e32 v0, 0
	s_addc_u32 s75, s27, 0
	s_mov_b32 s76, -2
	v_mov_b32_e32 v1, v0
	v_mov_b32_e32 v2, v0
	v_mov_b32_e32 v3, v0
	v_mov_b32_e32 v4, v0
	v_mov_b32_e32 v5, v0
	v_mov_b32_e32 v6, v0
	v_mov_b32_e32 v7, v0
	v_mov_b32_e32 v16, v0
	v_mov_b32_e32 v17, v0
	v_mov_b32_e32 v18, v0
	v_mov_b32_e32 v19, v0
	v_mov_b32_e32 v20, v0
	v_mov_b32_e32 v21, v0
	v_mov_b32_e32 v22, v0
	v_mov_b32_e32 v23, v0
	v_mov_b32_e32 v32, v0
	v_mov_b32_e32 v33, v0
	v_mov_b32_e32 v34, v0
	v_mov_b32_e32 v35, v0
	s_waitcnt vmcnt(0)
	v_mov_b32_e32 v36, v0
	v_mov_b32_e32 v37, v0
	v_mov_b32_e32 v38, v0
	v_mov_b32_e32 v39, v0
	v_mov_b32_e32 v48, v0
	v_mov_b32_e32 v49, v0
	v_mov_b32_e32 v50, v0
	v_mov_b32_e32 v51, v0
	v_mov_b32_e32 v52, v0
	v_mov_b32_e32 v53, v0
	v_mov_b32_e32 v54, v0
	v_mov_b32_e32 v55, v0
	v_mov_b32_e32 v8, v0
	v_mov_b32_e32 v9, v0
	v_mov_b32_e32 v10, v0
	v_mov_b32_e32 v11, v0
	v_mov_b32_e32 v12, v0
	v_mov_b32_e32 v13, v0
	v_mov_b32_e32 v14, v0
	v_mov_b32_e32 v15, v0
	v_mov_b32_e32 v24, v0
	v_mov_b32_e32 v25, v0
	v_mov_b32_e32 v26, v0
	v_mov_b32_e32 v27, v0
	v_mov_b32_e32 v28, v0
	v_mov_b32_e32 v29, v0
	v_mov_b32_e32 v30, v0
	v_mov_b32_e32 v31, v0
	v_mov_b32_e32 v40, v0
	v_mov_b32_e32 v41, v0
	v_mov_b32_e32 v42, v0
	v_mov_b32_e32 v43, v0
	v_mov_b32_e32 v44, v0
	v_mov_b32_e32 v45, v0
	v_mov_b32_e32 v46, v0
	v_mov_b32_e32 v47, v0
	v_mov_b32_e32 v56, v0
	v_mov_b32_e32 v57, v0
	v_mov_b32_e32 v58, v0
	v_mov_b32_e32 v59, v0
	v_mov_b32_e32 v60, v0
	v_mov_b32_e32 v61, v0
	v_mov_b32_e32 v62, v0
	v_mov_b32_e32 v63, v0
	v_mov_b32_e32 v64, v0
	v_mov_b32_e32 v65, v0
	v_mov_b32_e32 v66, v0
	v_mov_b32_e32 v67, v0
	v_mov_b32_e32 v68, v0
	v_mov_b32_e32 v69, v0
	v_mov_b32_e32 v70, v0
	v_mov_b32_e32 v71, v0
	v_mov_b32_e32 v80, v0
	v_mov_b32_e32 v81, v0
	v_mov_b32_e32 v82, v0
	v_mov_b32_e32 v83, v0
	v_mov_b32_e32 v84, v0
	v_mov_b32_e32 v85, v0
	v_mov_b32_e32 v86, v0
	v_mov_b32_e32 v87, v0
	v_mov_b32_e32 v96, v0
	v_mov_b32_e32 v97, v0
	v_mov_b32_e32 v98, v0
	v_mov_b32_e32 v99, v0
	v_mov_b32_e32 v100, v0
	v_mov_b32_e32 v101, v0
	v_mov_b32_e32 v102, v0
	v_mov_b32_e32 v103, v0
	v_mov_b32_e32 v112, v0
	v_mov_b32_e32 v113, v0
	v_mov_b32_e32 v114, v0
	v_mov_b32_e32 v115, v0
	v_mov_b32_e32 v116, v0
	v_mov_b32_e32 v117, v0
	v_mov_b32_e32 v118, v0
	v_mov_b32_e32 v119, v0
	v_mov_b32_e32 v72, v0
	v_mov_b32_e32 v73, v0
	v_mov_b32_e32 v74, v0
	v_mov_b32_e32 v75, v0
	v_mov_b32_e32 v76, v0
	v_mov_b32_e32 v77, v0
	v_mov_b32_e32 v78, v0
	v_mov_b32_e32 v79, v0
	v_mov_b32_e32 v88, v0
	v_mov_b32_e32 v89, v0
	v_mov_b32_e32 v90, v0
	v_mov_b32_e32 v91, v0
	v_mov_b32_e32 v92, v0
	v_mov_b32_e32 v93, v0
	v_mov_b32_e32 v94, v0
	v_mov_b32_e32 v95, v0
	v_mov_b32_e32 v104, v0
	v_mov_b32_e32 v105, v0
	v_mov_b32_e32 v106, v0
	v_mov_b32_e32 v107, v0
	v_mov_b32_e32 v108, v0
	v_mov_b32_e32 v109, v0
	v_mov_b32_e32 v110, v0
	v_mov_b32_e32 v111, v0
	v_mov_b32_e32 v120, v0
	v_mov_b32_e32 v121, v0
	v_mov_b32_e32 v122, v0
	v_mov_b32_e32 v123, v0
	v_mov_b32_e32 v124, v0
	v_mov_b32_e32 v125, v0
	v_mov_b32_e32 v126, v0
	v_mov_b32_e32 v127, v0
	s_lshl_b32 s97, s22, 8
	v_add_u32_e32 v252, s97, v141
	v_mov_b32_e32 v253, 0
	v_lshlrev_b64 v[252:253], 6, v[252:253]
	v_lshl_add_u64 v[254:255], v[128:129], 0, v[252:253]
	global_load_dwordx4 v[236:239], v[254:255], off
	global_load_dwordx4 v[240:243], v[254:255], off offset:1024
	global_load_dwordx4 v[244:247], v[254:255], off offset:2048
	global_load_dwordx4 v[248:251], v[254:255], off offset:3072

.LBB0_1360:
	s_lshl_b32 s13, s22, 8
	v_add_u32_e32 v138, s13, v141
	v_ashrrev_i32_e32 v139, 31, v138
	v_or_b32_e32 v154, 16, v138
	v_lshlrev_b64 v[152:153], 6, v[138:139]
	v_ashrrev_i32_e32 v155, 31, v154
	v_lshl_add_u64 v[152:153], v[128:129], 0, v[152:153]
	v_lshlrev_b64 v[154:155], 6, v[154:155]
	v_lshl_add_u64 v[158:159], v[128:129], 0, v[154:155]
	v_mov_b32_e32 v154, v236
	v_mov_b32_e32 v155, v237
	v_mov_b32_e32 v156, v238
	v_mov_b32_e32 v157, v239
	v_mov_b32_e32 v168, v240
	v_mov_b32_e32 v169, v241
	v_mov_b32_e32 v170, v242
	v_mov_b32_e32 v171, v243
	v_or_b32_e32 v152, 32, v138
	v_ashrrev_i32_e32 v153, 31, v152
	v_lshlrev_b64 v[152:153], 6, v[152:153]
	v_lshl_add_u64 v[152:153], v[128:129], 0, v[152:153]
	v_mov_b32_e32 v172, v244
	v_mov_b32_e32 v173, v245
	v_mov_b32_e32 v174, v246
	v_mov_b32_e32 v175, v247
	v_or_b32_e32 v152, 48, v138
	v_ashrrev_i32_e32 v153, 31, v152
	v_lshlrev_b64 v[152:153], 6, v[152:153]
	v_lshl_add_u64 v[152:153], v[128:129], 0, v[152:153]
	v_mov_b32_e32 v176, v248
	v_mov_b32_e32 v177, v249
	v_mov_b32_e32 v178, v250
	v_mov_b32_e32 v179, v251
	v_add_u32_e32 v252, 0x80, v138
	v_mov_b32_e32 v253, 0
	v_lshlrev_b64 v[252:253], 6, v[252:253]
	v_lshl_add_u64 v[252:253], v[128:129], 0, v[252:253]
	global_load_dwordx4 v[236:239], v[252:253], off
	global_load_dwordx4 v[240:243], v[252:253], off offset:1024
	global_load_dwordx4 v[244:247], v[252:253], off offset:2048
	global_load_dwordx4 v[248:251], v[252:253], off offset:3072
	v_and_b32_e32 v140, 64, v150
	v_xor_b32_e32 v139, 16, v150
	v_add_u32_e32 v140, 64, v140
	v_xor_b32_e32 v152, 32, v150
	v_cmp_lt_i32_e32 vcc, v139, v140
	v_lshl_or_b32 v158, s71, 7, v146
	v_ashrrev_i32_e32 v159, 31, v158
	v_cndmask_b32_e32 v139, v150, v139, vcc
	v_cmp_lt_i32_e32 vcc, v152, v140
	v_mov_b32_e32 v180, v155
	v_mov_b32_e32 v181, v156
	v_mov_b32_e32 v155, v157
	v_cndmask_b32_e32 v140, v150, v152, vcc
	v_pk_add_f32 v[154:155], v[180:181], v[154:155]
	v_lshlrev_b32_e32 v152, 2, v139
	v_lshlrev_b32_e32 v139, 2, v140
	v_mov_b32_e32 v156, v169
	v_mov_b32_e32 v157, v170
	v_mov_b32_e32 v169, v171
	v_add_f32_e32 v140, v154, v155
	v_mov_b32_e32 v170, v173
	v_mov_b32_e32 v171, v174
	v_mov_b32_e32 v173, v175
	v_pk_add_f32 v[154:155], v[156:157], v[168:169]
	ds_bpermute_b32 v153, v152, v140
	v_mov_b32_e32 v174, v177
	v_mov_b32_e32 v175, v178
	v_mov_b32_e32 v177, v179
	v_pk_add_f32 v[156:157], v[170:171], v[172:173]
	v_add_f32_e32 v154, v154, v155
	v_pk_add_f32 v[168:169], v[174:175], v[176:177]
	v_add_f32_e32 v155, v156, v157
	ds_bpermute_b32 v157, v152, v154
	v_add_f32_e32 v156, v168, v169
	ds_bpermute_b32 v168, v152, v155
	ds_bpermute_b32 v169, v152, v156
	s_waitcnt lgkmcnt(3)
	v_add_f32_e32 v140, v140, v153
	ds_bpermute_b32 v153, v139, v140
	s_waitcnt lgkmcnt(3)
	v_add_f32_e32 v154, v154, v157
	ds_bpermute_b32 v157, v139, v154
	s_waitcnt lgkmcnt(3)
	v_add_f32_e32 v155, v155, v168
	s_waitcnt lgkmcnt(2)
	v_add_f32_e32 v156, v156, v169
	ds_bpermute_b32 v168, v139, v155
	ds_bpermute_b32 v169, v139, v156
	s_waitcnt lgkmcnt(3)
	v_add_f32_e32 v140, v140, v153
	v_fmamk_f32 v140, v140, 0x3a800000, v151
	s_waitcnt lgkmcnt(2)
	v_add_f32_e32 v153, v154, v157
	v_rsq_f32_e32 v154, v140
	s_waitcnt lgkmcnt(1)
	v_add_f32_e32 v155, v155, v168
	s_waitcnt lgkmcnt(0)
	v_add_f32_e32 v156, v156, v169
	v_fmamk_f32 v140, v153, 0x3a800000, v151
	v_fmamk_f32 v153, v155, 0x3a800000, v151
	v_fmamk_f32 v155, v156, 0x3a800000, v151
	v_pk_mul_f32 v[126:127], v[126:127], v[154:155] op_sel_hi:[1,0]
	v_pk_mul_f32 v[124:125], v[124:125], v[154:155] op_sel_hi:[1,0]
	v_pk_mul_f32 v[118:119], v[118:119], v[154:155] op_sel_hi:[1,0]
	v_pk_mul_f32 v[116:117], v[116:117], v[154:155] op_sel_hi:[1,0]
	v_mul_f32_e32 v118, v126, v118
	v_mul_f32_e32 v116, v124, v116
	v_mul_f32_e32 v124, 0xbfb8aa3b, v124
	v_mul_f32_e32 v117, v125, v117
	v_mul_f32_e32 v125, 0xbfb8aa3b, v125
	v_mul_f32_e32 v126, 0xbfb8aa3b, v126
	v_mul_f32_e32 v119, v127, v119
	v_mul_f32_e32 v127, 0xbfb8aa3b, v127
	v_exp_f32_e32 v124, v124
	v_exp_f32_e32 v125, v125
	v_exp_f32_e32 v126, v126
	v_exp_f32_e32 v127, v127
	v_pk_mul_f32 v[120:121], v[120:121], v[154:155] op_sel_hi:[1,0]
	v_pk_mul_f32 v[122:123], v[122:123], v[154:155] op_sel_hi:[1,0]
	v_pk_mul_f32 v[114:115], v[114:115], v[154:155] op_sel_hi:[1,0]
	v_pk_mul_f32 v[112:113], v[112:113], v[154:155] op_sel_hi:[1,0]
	v_mul_f32_e32 v154, 0xbfb8aa3b, v121
	v_add_f32_e32 v124, 1.0, v124
	v_add_f32_e32 v125, 1.0, v125
	v_add_f32_e32 v126, 1.0, v126
	v_exp_f32_e32 v154, v154
	v_add_f32_e32 v127, 1.0, v127
	v_rcp_f32_e32 v124, v124
	v_rcp_f32_e32 v125, v125
	v_rcp_f32_e32 v126, v126
	v_rcp_f32_e32 v127, v127
	v_rsq_f32_e32 v168, v153
	v_mul_f32_e32 v153, 0xbfb8aa3b, v120
	v_exp_f32_e32 v153, v153
	v_add_f32_e32 v154, 1.0, v154
	v_mul_f32_e32 v116, v116, v124
	v_mul_f32_e32 v117, v117, v125
	v_mul_f32_e32 v118, v118, v126
	v_mul_f32_e32 v119, v119, v127
	v_cvt_pk_bf16_f32 v116, v116, v117
	v_cvt_pk_bf16_f32 v117, v118, v119
	v_rcp_f32_e32 v118, v154
	v_add_f32_e32 v153, 1.0, v153
	v_mul_f32_e32 v113, v121, v113
	v_rcp_f32_e32 v153, v153
	v_mul_f32_e32 v113, v113, v118
	v_mul_f32_e32 v118, 0xbfb8aa3b, v122
	v_exp_f32_e32 v119, v118
	v_mul_f32_e32 v118, 0xbfb8aa3b, v123
	v_mul_f32_e32 v112, v120, v112
	v_exp_f32_e32 v120, v118
	v_mul_f32_e32 v112, v112, v153
	v_cvt_pk_bf16_f32 v118, v112, v113
	v_add_f32_e32 v112, 1.0, v119
	v_rcp_f32_e32 v112, v112
	v_add_f32_e32 v113, 1.0, v120
	v_rcp_f32_e32 v113, v113
	v_mul_f32_e32 v114, v122, v114
	v_rsq_f32_e32 v156, v140
	v_mul_f32_e32 v112, v114, v112
	v_mul_f32_e32 v114, v123, v115
	v_mul_f32_e32 v113, v114, v113
	v_cvt_pk_bf16_f32 v119, v112, v113
	v_mov_b64_e32 v[112:113], s[36:37]
	v_mad_i64_i32 v[120:121], s[24:25], v138, s70, v[112:113]
	v_lshlrev_b64 v[114:115], 1, v[158:159]
	v_lshl_add_u64 v[120:121], v[120:121], 0, v[114:115]
	v_pk_mul_f32 v[108:109], v[108:109], v[156:157] op_sel_hi:[1,0]
	global_store_dwordx4 v[120:121], v[116:119], off
	v_pk_mul_f32 v[100:101], v[100:101], v[156:157] op_sel_hi:[1,0]
	v_pk_mul_f32 v[110:111], v[110:111], v[156:157] op_sel_hi:[1,0]
	v_pk_mul_f32 v[116:117], v[98:99], v[156:157] op_sel_hi:[1,0]
	v_mul_f32_e32 v98, 0xbfb8aa3b, v108
	v_exp_f32_e32 v119, v98
	v_mul_f32_e32 v98, 0xbfb8aa3b, v109
	v_exp_f32_e32 v120, v98
	v_pk_mul_f32 v[98:99], v[96:97], v[156:157] op_sel_hi:[1,0]
	v_add_f32_e32 v96, 1.0, v119
	v_rcp_f32_e32 v96, v96
	v_add_f32_e32 v97, 1.0, v120
	v_rcp_f32_e32 v97, v97
	v_mul_f32_e32 v100, v108, v100
	v_mul_f32_e32 v96, v100, v96
	v_mul_f32_e32 v100, v109, v101
	v_mul_f32_e32 v97, v100, v97
	v_mul_f32_e32 v100, 0xbfb8aa3b, v110
	v_exp_f32_e32 v100, v100
	v_mul_f32_e32 v101, 0xbfb8aa3b, v111
	v_exp_f32_e32 v101, v101
	v_cvt_pk_bf16_f32 v96, v96, v97
	v_add_f32_e32 v97, 1.0, v100
	v_rcp_f32_e32 v97, v97
	v_add_f32_e32 v100, 1.0, v101
	v_rcp_f32_e32 v100, v100
	v_pk_mul_f32 v[102:103], v[102:103], v[156:157] op_sel_hi:[1,0]
	v_pk_mul_f32 v[104:105], v[104:105], v[156:157] op_sel_hi:[1,0]
	v_mul_f32_e32 v101, v110, v102
	v_mul_f32_e32 v97, v101, v97
	v_mul_f32_e32 v101, v111, v103
	v_mul_f32_e32 v100, v101, v100
	v_mul_f32_e32 v101, 0xbfb8aa3b, v104
	v_exp_f32_e32 v101, v101
	v_mul_f32_e32 v102, 0xbfb8aa3b, v105
	v_exp_f32_e32 v102, v102
	v_cvt_pk_bf16_f32 v97, v97, v100
	v_add_f32_e32 v100, 1.0, v101
	v_rcp_f32_e32 v100, v100
	v_add_f32_e32 v101, 1.0, v102
	v_rcp_f32_e32 v101, v101
	v_pk_mul_f32 v[106:107], v[106:107], v[156:157] op_sel_hi:[1,0]
	v_mul_f32_e32 v98, v104, v98
	v_mul_f32_e32 v98, v98, v100
	v_mul_f32_e32 v99, v105, v99
	v_mul_f32_e32 v100, 0xbfb8aa3b, v106
	v_mul_f32_e32 v99, v99, v101
	v_exp_f32_e32 v100, v100
	v_mul_f32_e32 v101, 0xbfb8aa3b, v107
	v_exp_f32_e32 v101, v101
	v_cvt_pk_bf16_f32 v98, v98, v99
	v_add_f32_e32 v99, 1.0, v100
	v_rcp_f32_e32 v99, v99
	v_add_f32_e32 v100, 1.0, v101
	v_rcp_f32_e32 v100, v100
	v_mul_f32_e32 v101, v106, v116
	v_mul_f32_e32 v99, v101, v99
	v_mul_f32_e32 v101, v107, v117
	v_add_u32_e32 v118, s13, v143
	v_mul_f32_e32 v100, v101, v100
	v_cvt_pk_bf16_f32 v99, v99, v100
	v_mad_i64_i32 v[100:101], s[24:25], v118, s70, v[112:113]
	v_lshl_add_u64 v[100:101], v[100:101], 0, v[114:115]
	v_pk_mul_f32 v[92:93], v[92:93], v[168:169] op_sel_hi:[1,0]
	global_store_dwordx4 v[100:101], v[96:99], off
	v_pk_mul_f32 v[84:85], v[84:85], v[168:169] op_sel_hi:[1,0]
	v_pk_mul_f32 v[94:95], v[94:95], v[168:169] op_sel_hi:[1,0]
	v_pk_mul_f32 v[96:97], v[82:83], v[168:169] op_sel_hi:[1,0]
	v_mul_f32_e32 v82, 0xbfb8aa3b, v92
	v_exp_f32_e32 v99, v82
	v_mul_f32_e32 v82, 0xbfb8aa3b, v93
	v_exp_f32_e32 v100, v82
	v_pk_mul_f32 v[82:83], v[80:81], v[168:169] op_sel_hi:[1,0]
	v_add_f32_e32 v80, 1.0, v99
	v_rcp_f32_e32 v80, v80
	v_add_f32_e32 v81, 1.0, v100
	v_rcp_f32_e32 v81, v81
	v_mul_f32_e32 v84, v92, v84
	v_mul_f32_e32 v80, v84, v80
	v_mul_f32_e32 v84, v93, v85
	v_mul_f32_e32 v81, v84, v81
	v_mul_f32_e32 v84, 0xbfb8aa3b, v94
	v_exp_f32_e32 v84, v84
	v_mul_f32_e32 v85, 0xbfb8aa3b, v95
	v_exp_f32_e32 v85, v85
	v_cvt_pk_bf16_f32 v80, v80, v81
	v_add_f32_e32 v81, 1.0, v84
	v_rcp_f32_e32 v81, v81
	v_add_f32_e32 v84, 1.0, v85
	v_rcp_f32_e32 v84, v84
	v_pk_mul_f32 v[86:87], v[86:87], v[168:169] op_sel_hi:[1,0]
	v_pk_mul_f32 v[88:89], v[88:89], v[168:169] op_sel_hi:[1,0]
	v_mul_f32_e32 v85, v94, v86
	v_mul_f32_e32 v81, v85, v81
	v_mul_f32_e32 v85, v95, v87
	v_mul_f32_e32 v84, v85, v84
	v_mul_f32_e32 v85, 0xbfb8aa3b, v88
	v_exp_f32_e32 v85, v85
	v_mul_f32_e32 v86, 0xbfb8aa3b, v89
	v_exp_f32_e32 v86, v86
	v_cvt_pk_bf16_f32 v81, v81, v84
	v_add_f32_e32 v84, 1.0, v85
	v_rcp_f32_e32 v84, v84
	v_add_f32_e32 v85, 1.0, v86
	v_rcp_f32_e32 v85, v85
	v_pk_mul_f32 v[90:91], v[90:91], v[168:169] op_sel_hi:[1,0]
	v_mul_f32_e32 v82, v88, v82
	v_mul_f32_e32 v82, v82, v84
	v_mul_f32_e32 v83, v89, v83
	v_mul_f32_e32 v84, 0xbfb8aa3b, v90
	v_mul_f32_e32 v83, v83, v85
	v_exp_f32_e32 v84, v84
	v_mul_f32_e32 v85, 0xbfb8aa3b, v91
	v_exp_f32_e32 v85, v85
	v_cvt_pk_bf16_f32 v82, v82, v83
	v_add_f32_e32 v83, 1.0, v84
	v_rcp_f32_e32 v83, v83
	v_add_f32_e32 v84, 1.0, v85
	v_rcp_f32_e32 v84, v84
	v_rsq_f32_e32 v140, v155
	v_mul_f32_e32 v85, v90, v96
	v_mul_f32_e32 v83, v85, v83
	v_mul_f32_e32 v85, v91, v97
	v_add_u32_e32 v98, s13, v144
	v_mul_f32_e32 v84, v85, v84
	v_cvt_pk_bf16_f32 v83, v83, v84
	v_mad_i64_i32 v[84:85], s[24:25], v98, s70, v[112:113]
	v_lshl_add_u64 v[84:85], v[84:85], 0, v[114:115]
	v_pk_mul_f32 v[76:77], v[76:77], v[140:141] op_sel_hi:[1,0]
	global_store_dwordx4 v[84:85], v[80:83], off
	v_pk_mul_f32 v[68:69], v[68:69], v[140:141] op_sel_hi:[1,0]
	v_pk_mul_f32 v[78:79], v[78:79], v[140:141] op_sel_hi:[1,0]
	v_pk_mul_f32 v[80:81], v[66:67], v[140:141] op_sel_hi:[1,0]
	v_mul_f32_e32 v66, 0xbfb8aa3b, v76
	v_exp_f32_e32 v83, v66
	v_mul_f32_e32 v66, 0xbfb8aa3b, v77
	v_exp_f32_e32 v84, v66
	v_pk_mul_f32 v[66:67], v[64:65], v[140:141] op_sel_hi:[1,0]
	v_add_f32_e32 v64, 1.0, v83
	v_rcp_f32_e32 v64, v64
	v_add_f32_e32 v65, 1.0, v84
	v_rcp_f32_e32 v65, v65
	v_mul_f32_e32 v68, v76, v68
	v_mul_f32_e32 v64, v68, v64
	v_mul_f32_e32 v68, v77, v69
	v_mul_f32_e32 v65, v68, v65
	v_mul_f32_e32 v68, 0xbfb8aa3b, v78
	v_exp_f32_e32 v68, v68
	v_mul_f32_e32 v69, 0xbfb8aa3b, v79
	v_exp_f32_e32 v69, v69
	v_cvt_pk_bf16_f32 v64, v64, v65
	v_add_f32_e32 v65, 1.0, v68
	v_rcp_f32_e32 v65, v65
	v_add_f32_e32 v68, 1.0, v69
	v_rcp_f32_e32 v68, v68
	v_pk_mul_f32 v[70:71], v[70:71], v[140:141] op_sel_hi:[1,0]
	v_pk_mul_f32 v[72:73], v[72:73], v[140:141] op_sel_hi:[1,0]
	v_mul_f32_e32 v69, v78, v70
	v_mul_f32_e32 v65, v69, v65
	v_mul_f32_e32 v69, v79, v71
	v_mul_f32_e32 v68, v69, v68
	v_mul_f32_e32 v69, 0xbfb8aa3b, v72
	v_exp_f32_e32 v69, v69
	v_mul_f32_e32 v70, 0xbfb8aa3b, v73
	v_exp_f32_e32 v70, v70
	v_cvt_pk_bf16_f32 v65, v65, v68
	v_add_f32_e32 v68, 1.0, v69
	v_rcp_f32_e32 v68, v68
	v_add_f32_e32 v69, 1.0, v70
	v_rcp_f32_e32 v69, v69
	v_pk_mul_f32 v[74:75], v[74:75], v[140:141] op_sel_hi:[1,0]
	v_mul_f32_e32 v66, v72, v66
	v_mul_f32_e32 v66, v66, v68
	v_mul_f32_e32 v67, v73, v67
	v_mul_f32_e32 v68, 0xbfb8aa3b, v74
	v_mul_f32_e32 v67, v67, v69
	v_exp_f32_e32 v68, v68
	v_mul_f32_e32 v69, 0xbfb8aa3b, v75
	v_exp_f32_e32 v69, v69
	v_cvt_pk_bf16_f32 v66, v66, v67
	v_add_f32_e32 v67, 1.0, v68
	v_rcp_f32_e32 v67, v67
	v_add_f32_e32 v68, 1.0, v69
	v_rcp_f32_e32 v68, v68
	v_mul_f32_e32 v69, v74, v80
	v_mul_f32_e32 v67, v69, v67
	v_mul_f32_e32 v69, v75, v81
	v_add_u32_e32 v82, s13, v145
	v_mul_f32_e32 v68, v69, v68
	v_cvt_pk_bf16_f32 v67, v67, v68
	v_mad_i64_i32 v[68:69], s[24:25], v82, s70, v[112:113]
	v_add_u32_e32 v88, 0x80, v138
	v_lshl_add_u64 v[68:69], v[68:69], 0, v[114:115]
	v_ashrrev_i32_e32 v89, 31, v88
	global_store_dwordx4 v[68:69], v[64:67], off
	v_add_u32_e32 v70, 0x90, v138
	v_ashrrev_i32_e32 v71, 31, v70
	v_lshlrev_b64 v[64:65], 6, v[88:89]
	v_lshl_add_u64 v[64:65], v[128:129], 0, v[64:65]
	s_waitcnt vmcnt(4)
	v_mov_b32_e32 v72, v236
	v_mov_b32_e32 v73, v237
	v_mov_b32_e32 v74, v238
	v_mov_b32_e32 v75, v239
	v_lshlrev_b64 v[64:65], 6, v[70:71]
	v_lshl_add_u64 v[64:65], v[128:129], 0, v[64:65]
	v_mov_b32_e32 v76, v240
	v_mov_b32_e32 v77, v241
	v_mov_b32_e32 v78, v242
	v_mov_b32_e32 v79, v243
	v_add_u32_e32 v66, 0xa0, v138
	v_ashrrev_i32_e32 v67, 31, v66
	v_lshlrev_b64 v[64:65], 6, v[66:67]
	v_lshl_add_u64 v[64:65], v[128:129], 0, v[64:65]
	v_mov_b32_e32 v80, v244
	v_mov_b32_e32 v81, v245
	v_mov_b32_e32 v82, v246
	v_mov_b32_e32 v83, v247
	v_add_u32_e32 v64, 0xb0, v138
	v_ashrrev_i32_e32 v65, 31, v64
	v_lshlrev_b64 v[68:69], 6, v[64:65]
	v_lshl_add_u64 v[68:69], v[128:129], 0, v[68:69]
	v_mov_b32_e32 v84, v248
	v_mov_b32_e32 v85, v249
	v_mov_b32_e32 v86, v250
	v_mov_b32_e32 v87, v251
	s_andn2_b64 vcc, exec, s[0:1]
	s_mov_b64 s[0:1], -1
	v_mov_b32_e32 v68, v73
	v_mov_b32_e32 v69, v74
	v_mov_b32_e32 v73, v75
	v_pk_add_f32 v[68:69], v[68:69], v[72:73]
	s_nop 0
	v_add_f32_e32 v65, v68, v69
	ds_bpermute_b32 v67, v152, v65
	v_mov_b32_e32 v68, v77
	v_mov_b32_e32 v69, v78
	v_mov_b32_e32 v77, v79
	v_pk_add_f32 v[68:69], v[68:69], v[76:77]
	s_waitcnt lgkmcnt(0)
	v_add_f32_e32 v65, v65, v67
	ds_bpermute_b32 v67, v139, v65
	v_add_f32_e32 v68, v68, v69
	ds_bpermute_b32 v69, v152, v68
	s_waitcnt lgkmcnt(1)
	v_add_f32_e32 v65, v65, v67
	v_fmamk_f32 v65, v65, 0x3a800000, v151
	v_rsq_f32_e32 v72, v65
	s_waitcnt lgkmcnt(0)
	v_add_f32_e32 v65, v68, v69
	v_mov_b32_e32 v68, v81
	v_mov_b32_e32 v69, v82
	v_mov_b32_e32 v81, v83
	v_pk_add_f32 v[68:69], v[68:69], v[80:81]
	ds_bpermute_b32 v67, v139, v65
	v_add_f32_e32 v71, v68, v69
	v_mov_b32_e32 v68, v85
	v_mov_b32_e32 v69, v86
	v_mov_b32_e32 v85, v87
	ds_bpermute_b32 v73, v152, v71
	v_pk_add_f32 v[68:69], v[68:69], v[84:85]
	s_waitcnt lgkmcnt(1)
	v_add_f32_e32 v65, v65, v67
	v_add_f32_e32 v68, v68, v69
	ds_bpermute_b32 v69, v152, v68
	s_waitcnt lgkmcnt(1)
	v_add_f32_e32 v67, v71, v73
	ds_bpermute_b32 v71, v139, v67
	v_fmamk_f32 v65, v65, 0x3a800000, v151
	v_rsq_f32_e32 v74, v65
	s_waitcnt lgkmcnt(1)
	v_add_f32_e32 v68, v68, v69
	ds_bpermute_b32 v69, v139, v68
	s_waitcnt lgkmcnt(1)
	v_add_f32_e32 v65, v67, v71
	v_fmamk_f32 v65, v65, 0x3a800000, v151
	v_rsq_f32_e32 v76, v65
	v_pk_mul_f32 v[60:61], v[60:61], v[72:73] op_sel_hi:[1,0]
	s_waitcnt lgkmcnt(0)
	v_add_f32_e32 v65, v68, v69
	v_fmamk_f32 v65, v65, 0x3a800000, v151
	v_pk_mul_f32 v[78:79], v[50:51], v[72:73] op_sel_hi:[1,0]
	v_mul_f32_e32 v50, 0xbfb8aa3b, v60
	v_rsq_f32_e32 v68, v65
	v_exp_f32_e32 v65, v50
	v_mul_f32_e32 v50, 0xbfb8aa3b, v61
	v_exp_f32_e32 v67, v50
	v_pk_mul_f32 v[50:51], v[48:49], v[72:73] op_sel_hi:[1,0]
	v_add_f32_e32 v48, 1.0, v65
	v_rcp_f32_e32 v48, v48
	v_add_f32_e32 v49, 1.0, v67
	v_rcp_f32_e32 v49, v49
	v_pk_mul_f32 v[52:53], v[52:53], v[72:73] op_sel_hi:[1,0]
	v_pk_mul_f32 v[62:63], v[62:63], v[72:73] op_sel_hi:[1,0]
	v_mul_f32_e32 v52, v60, v52
	v_mul_f32_e32 v48, v52, v48
	v_mul_f32_e32 v52, v61, v53
	v_mul_f32_e32 v49, v52, v49
	v_mul_f32_e32 v52, 0xbfb8aa3b, v62
	v_exp_f32_e32 v52, v52
	v_mul_f32_e32 v53, 0xbfb8aa3b, v63
	v_exp_f32_e32 v53, v53
	v_cvt_pk_bf16_f32 v48, v48, v49
	v_add_f32_e32 v49, 1.0, v52
	v_rcp_f32_e32 v49, v49
	v_add_f32_e32 v52, 1.0, v53
	v_rcp_f32_e32 v52, v52
	v_pk_mul_f32 v[54:55], v[54:55], v[72:73] op_sel_hi:[1,0]
	v_pk_mul_f32 v[56:57], v[56:57], v[72:73] op_sel_hi:[1,0]
	v_mul_f32_e32 v53, v62, v54
	v_mul_f32_e32 v49, v53, v49
	v_mul_f32_e32 v53, v63, v55
	v_mul_f32_e32 v52, v53, v52
	v_mul_f32_e32 v53, 0xbfb8aa3b, v56
	v_exp_f32_e32 v53, v53
	v_mul_f32_e32 v54, 0xbfb8aa3b, v57
	v_exp_f32_e32 v54, v54
	v_cvt_pk_bf16_f32 v49, v49, v52
	v_add_f32_e32 v52, 1.0, v53
	v_rcp_f32_e32 v52, v52
	v_add_f32_e32 v53, 1.0, v54
	v_rcp_f32_e32 v53, v53
	v_pk_mul_f32 v[58:59], v[58:59], v[72:73] op_sel_hi:[1,0]
	v_mul_f32_e32 v50, v56, v50
	v_mul_f32_e32 v50, v50, v52
	v_mul_f32_e32 v51, v57, v51
	v_mul_f32_e32 v52, 0xbfb8aa3b, v58
	v_mul_f32_e32 v51, v51, v53
	v_exp_f32_e32 v52, v52
	v_mul_f32_e32 v53, 0xbfb8aa3b, v59
	v_exp_f32_e32 v53, v53
	v_cvt_pk_bf16_f32 v50, v50, v51
	v_add_f32_e32 v51, 1.0, v52
	v_rcp_f32_e32 v51, v51
	v_add_f32_e32 v52, 1.0, v53
	v_rcp_f32_e32 v52, v52
	v_mul_f32_e32 v53, v58, v78
	v_mul_f32_e32 v51, v53, v51
	v_mul_f32_e32 v53, v59, v79
	v_mul_f32_e32 v52, v53, v52
	v_cvt_pk_bf16_f32 v51, v51, v52
	v_mad_i64_i32 v[52:53], s[24:25], v88, s70, v[112:113]
	v_lshl_add_u64 v[52:53], v[52:53], 0, v[114:115]
	v_pk_mul_f32 v[44:45], v[44:45], v[74:75] op_sel_hi:[1,0]
	global_store_dwordx4 v[52:53], v[48:51], off
	v_pk_mul_f32 v[36:37], v[36:37], v[74:75] op_sel_hi:[1,0]
	v_pk_mul_f32 v[46:47], v[46:47], v[74:75] op_sel_hi:[1,0]
	v_pk_mul_f32 v[48:49], v[34:35], v[74:75] op_sel_hi:[1,0]
	v_mul_f32_e32 v34, 0xbfb8aa3b, v44
	v_exp_f32_e32 v50, v34
	v_mul_f32_e32 v34, 0xbfb8aa3b, v45
	v_exp_f32_e32 v51, v34
	v_pk_mul_f32 v[34:35], v[32:33], v[74:75] op_sel_hi:[1,0]
	v_add_f32_e32 v32, 1.0, v50
	v_rcp_f32_e32 v32, v32
	v_add_f32_e32 v33, 1.0, v51
	v_rcp_f32_e32 v33, v33
	v_mul_f32_e32 v36, v44, v36
	v_mul_f32_e32 v32, v36, v32
	v_mul_f32_e32 v36, v45, v37
	v_mul_f32_e32 v33, v36, v33
	v_mul_f32_e32 v36, 0xbfb8aa3b, v46
	v_exp_f32_e32 v36, v36
	v_mul_f32_e32 v37, 0xbfb8aa3b, v47
	v_exp_f32_e32 v37, v37
	v_cvt_pk_bf16_f32 v32, v32, v33
	v_add_f32_e32 v33, 1.0, v36
	v_rcp_f32_e32 v33, v33
	v_add_f32_e32 v36, 1.0, v37
	v_rcp_f32_e32 v36, v36
	v_pk_mul_f32 v[38:39], v[38:39], v[74:75] op_sel_hi:[1,0]
	v_pk_mul_f32 v[40:41], v[40:41], v[74:75] op_sel_hi:[1,0]
	v_mul_f32_e32 v37, v46, v38
	v_mul_f32_e32 v33, v37, v33
	v_mul_f32_e32 v37, v47, v39
	v_mul_f32_e32 v36, v37, v36
	v_mul_f32_e32 v37, 0xbfb8aa3b, v40
	v_exp_f32_e32 v37, v37
	v_mul_f32_e32 v38, 0xbfb8aa3b, v41
	v_exp_f32_e32 v38, v38
	v_cvt_pk_bf16_f32 v33, v33, v36
	v_add_f32_e32 v36, 1.0, v37
	v_rcp_f32_e32 v36, v36
	v_add_f32_e32 v37, 1.0, v38
	v_rcp_f32_e32 v37, v37
	v_pk_mul_f32 v[42:43], v[42:43], v[74:75] op_sel_hi:[1,0]
	v_mul_f32_e32 v34, v40, v34
	v_mul_f32_e32 v34, v34, v36
	v_mul_f32_e32 v35, v41, v35
	v_mul_f32_e32 v36, 0xbfb8aa3b, v42
	v_mul_f32_e32 v35, v35, v37
	v_exp_f32_e32 v36, v36
	v_mul_f32_e32 v37, 0xbfb8aa3b, v43
	v_exp_f32_e32 v37, v37
	v_cvt_pk_bf16_f32 v34, v34, v35
	v_add_f32_e32 v35, 1.0, v36
	v_rcp_f32_e32 v35, v35
	v_add_f32_e32 v36, 1.0, v37
	v_rcp_f32_e32 v36, v36
	v_mul_f32_e32 v37, v42, v48
	v_mul_f32_e32 v35, v37, v35
	v_mul_f32_e32 v37, v43, v49
	v_mul_f32_e32 v36, v37, v36
	v_cvt_pk_bf16_f32 v35, v35, v36
	v_mad_i64_i32 v[36:37], s[24:25], v70, s70, v[112:113]
	v_lshl_add_u64 v[36:37], v[36:37], 0, v[114:115]
	v_pk_mul_f32 v[28:29], v[28:29], v[76:77] op_sel_hi:[1,0]
	global_store_dwordx4 v[36:37], v[32:35], off
	v_pk_mul_f32 v[20:21], v[20:21], v[76:77] op_sel_hi:[1,0]
	v_pk_mul_f32 v[30:31], v[30:31], v[76:77] op_sel_hi:[1,0]
	v_pk_mul_f32 v[32:33], v[18:19], v[76:77] op_sel_hi:[1,0]
	v_mul_f32_e32 v18, 0xbfb8aa3b, v28
	v_exp_f32_e32 v34, v18
	v_mul_f32_e32 v18, 0xbfb8aa3b, v29
	v_exp_f32_e32 v35, v18
	v_pk_mul_f32 v[18:19], v[16:17], v[76:77] op_sel_hi:[1,0]
	v_add_f32_e32 v16, 1.0, v34
	v_rcp_f32_e32 v16, v16
	v_add_f32_e32 v17, 1.0, v35
	v_rcp_f32_e32 v17, v17
	v_mul_f32_e32 v20, v28, v20
	v_mul_f32_e32 v16, v20, v16
	v_mul_f32_e32 v20, v29, v21
	v_mul_f32_e32 v17, v20, v17
	v_mul_f32_e32 v20, 0xbfb8aa3b, v30
	v_exp_f32_e32 v20, v20
	v_mul_f32_e32 v21, 0xbfb8aa3b, v31
	v_exp_f32_e32 v21, v21
	v_cvt_pk_bf16_f32 v16, v16, v17
	v_add_f32_e32 v17, 1.0, v20
	v_rcp_f32_e32 v17, v17
	v_add_f32_e32 v20, 1.0, v21
	v_rcp_f32_e32 v20, v20
	v_pk_mul_f32 v[22:23], v[22:23], v[76:77] op_sel_hi:[1,0]
	v_pk_mul_f32 v[24:25], v[24:25], v[76:77] op_sel_hi:[1,0]
	v_mul_f32_e32 v21, v30, v22
	v_mul_f32_e32 v17, v21, v17
	v_mul_f32_e32 v21, v31, v23
	v_mul_f32_e32 v20, v21, v20
	v_mul_f32_e32 v21, 0xbfb8aa3b, v24
	v_exp_f32_e32 v21, v21
	v_mul_f32_e32 v22, 0xbfb8aa3b, v25
	v_exp_f32_e32 v22, v22
	v_cvt_pk_bf16_f32 v17, v17, v20
	v_add_f32_e32 v20, 1.0, v21
	v_rcp_f32_e32 v20, v20
	v_add_f32_e32 v21, 1.0, v22
	v_rcp_f32_e32 v21, v21
	v_pk_mul_f32 v[26:27], v[26:27], v[76:77] op_sel_hi:[1,0]
	v_mul_f32_e32 v18, v24, v18
	v_mul_f32_e32 v18, v18, v20
	v_mul_f32_e32 v19, v25, v19
	v_mul_f32_e32 v20, 0xbfb8aa3b, v26
	v_mul_f32_e32 v19, v19, v21
	v_exp_f32_e32 v20, v20
	v_mul_f32_e32 v21, 0xbfb8aa3b, v27
	v_exp_f32_e32 v21, v21
	v_cvt_pk_bf16_f32 v18, v18, v19
	v_add_f32_e32 v19, 1.0, v20
	v_rcp_f32_e32 v19, v19
	v_add_f32_e32 v20, 1.0, v21
	v_rcp_f32_e32 v20, v20
	v_mul_f32_e32 v21, v26, v32
	v_mul_f32_e32 v19, v21, v19
	v_mul_f32_e32 v21, v27, v33
	v_mul_f32_e32 v20, v21, v20
	v_cvt_pk_bf16_f32 v19, v19, v20
	v_mad_i64_i32 v[20:21], s[24:25], v66, s70, v[112:113]
	v_lshl_add_u64 v[20:21], v[20:21], 0, v[114:115]
	v_pk_mul_f32 v[12:13], v[12:13], v[68:69] op_sel_hi:[1,0]
	global_store_dwordx4 v[20:21], v[16:19], off
	v_pk_mul_f32 v[4:5], v[4:5], v[68:69] op_sel_hi:[1,0]
	v_pk_mul_f32 v[14:15], v[14:15], v[68:69] op_sel_hi:[1,0]
	v_pk_mul_f32 v[16:17], v[2:3], v[68:69] op_sel_hi:[1,0]
	v_mul_f32_e32 v2, 0xbfb8aa3b, v12
	v_exp_f32_e32 v18, v2
	v_mul_f32_e32 v2, 0xbfb8aa3b, v13
	v_exp_f32_e32 v19, v2
	v_pk_mul_f32 v[2:3], v[0:1], v[68:69] op_sel_hi:[1,0]
	v_add_f32_e32 v0, 1.0, v18
	v_rcp_f32_e32 v0, v0
	v_add_f32_e32 v1, 1.0, v19
	v_rcp_f32_e32 v1, v1
	v_mul_f32_e32 v4, v12, v4
	v_mul_f32_e32 v0, v4, v0
	v_mul_f32_e32 v4, v13, v5
	v_mul_f32_e32 v1, v4, v1
	v_mul_f32_e32 v4, 0xbfb8aa3b, v14
	v_exp_f32_e32 v4, v4
	v_mul_f32_e32 v5, 0xbfb8aa3b, v15
	v_exp_f32_e32 v5, v5
	v_cvt_pk_bf16_f32 v0, v0, v1
	v_add_f32_e32 v1, 1.0, v4
	v_rcp_f32_e32 v1, v1
	v_add_f32_e32 v4, 1.0, v5
	v_rcp_f32_e32 v4, v4
	v_pk_mul_f32 v[6:7], v[6:7], v[68:69] op_sel_hi:[1,0]
	v_pk_mul_f32 v[8:9], v[8:9], v[68:69] op_sel_hi:[1,0]
	v_mul_f32_e32 v5, v14, v6
	v_mul_f32_e32 v1, v5, v1
	v_mul_f32_e32 v5, v15, v7
	v_mul_f32_e32 v4, v5, v4
	v_mul_f32_e32 v5, 0xbfb8aa3b, v8
	v_exp_f32_e32 v5, v5
	v_mul_f32_e32 v6, 0xbfb8aa3b, v9
	v_exp_f32_e32 v6, v6
	v_cvt_pk_bf16_f32 v1, v1, v4
	v_add_f32_e32 v4, 1.0, v5
	v_rcp_f32_e32 v4, v4
	v_add_f32_e32 v5, 1.0, v6
	v_rcp_f32_e32 v5, v5
	v_pk_mul_f32 v[10:11], v[10:11], v[68:69] op_sel_hi:[1,0]
	v_mul_f32_e32 v2, v8, v2
	v_mul_f32_e32 v2, v2, v4
	v_mul_f32_e32 v3, v9, v3
	v_mul_f32_e32 v4, 0xbfb8aa3b, v10
	v_mul_f32_e32 v3, v3, v5
	v_exp_f32_e32 v4, v4
	v_mul_f32_e32 v5, 0xbfb8aa3b, v11
	v_exp_f32_e32 v5, v5
	v_cvt_pk_bf16_f32 v2, v2, v3
	v_add_f32_e32 v3, 1.0, v4
	v_rcp_f32_e32 v3, v3
	v_add_f32_e32 v4, 1.0, v5
	v_rcp_f32_e32 v4, v4
	v_mul_f32_e32 v5, v10, v16
	v_mul_f32_e32 v3, v5, v3
	v_mul_f32_e32 v5, v11, v17
	v_mul_f32_e32 v4, v5, v4
	v_cvt_pk_bf16_f32 v3, v3, v4
	v_mad_i64_i32 v[4:5], s[24:25], v64, s70, v[112:113]
	v_lshl_add_u64 v[4:5], v[4:5], 0, v[114:115]
	global_store_dwordx4 v[4:5], v[0:3], off
	s_cbranch_vccnz .LBB0_1353
	s_andn2_b64 vcc, exec, s[2:3]
	s_cbranch_vccnz .LBB0_1352
	s_barrier
	s_branch .LBB0_1352
